# P2 restructured: dilated kinds 1,2 and memory attention first, grid barrier, then kind-0 items each followed by a fused per-item combine; separate combine phase and its barrier removed
# baseline (speedup 1.0000x reference)
.LBB0_1268:
	ds_read_b128 v[170:173], v169
	ds_read_b128 v[174:177], v169 offset:16
	ds_read_b128 v[178:181], v169 offset:32
	ds_read_b128 v[182:185], v169 offset:48
	s_add_i32 s8, s8, -1
	s_waitcnt lgkmcnt(3)
	v_lshlrev_b32_e32 v186, 16, v170
	v_and_b32_e32 v187, 0xffff0000, v170
	v_lshlrev_b32_e32 v170, 16, v171
	v_and_b32_e32 v171, 0xffff0000, v171
	v_pk_add_f32 v[158:159], v[158:159], v[170:171]
	v_lshlrev_b32_e32 v170, 16, v172
	v_and_b32_e32 v171, 0xffff0000, v172
	v_pk_add_f32 v[156:157], v[156:157], v[170:171]
	v_lshlrev_b32_e32 v170, 16, v173
	v_and_b32_e32 v171, 0xffff0000, v173
	v_pk_add_f32 v[154:155], v[154:155], v[170:171]
	s_waitcnt lgkmcnt(2)
	v_lshlrev_b32_e32 v170, 16, v174
	v_and_b32_e32 v171, 0xffff0000, v174
	v_pk_add_f32 v[152:153], v[152:153], v[170:171]
	v_lshlrev_b32_e32 v170, 16, v175
	v_and_b32_e32 v171, 0xffff0000, v175
	v_pk_add_f32 v[150:151], v[150:151], v[170:171]
	v_lshlrev_b32_e32 v170, 16, v176
	v_and_b32_e32 v171, 0xffff0000, v176
	v_pk_add_f32 v[148:149], v[148:149], v[170:171]
	v_lshlrev_b32_e32 v170, 16, v177
	v_and_b32_e32 v171, 0xffff0000, v177
	v_pk_add_f32 v[146:147], v[146:147], v[170:171]
	s_waitcnt lgkmcnt(1)
	v_lshlrev_b32_e32 v170, 16, v178
	v_and_b32_e32 v171, 0xffff0000, v178
	v_pk_add_f32 v[144:145], v[144:145], v[170:171]
	v_lshlrev_b32_e32 v170, 16, v179
	v_and_b32_e32 v171, 0xffff0000, v179
	v_pk_add_f32 v[142:143], v[142:143], v[170:171]
	v_lshlrev_b32_e32 v170, 16, v180
	v_and_b32_e32 v171, 0xffff0000, v180
	v_pk_add_f32 v[140:141], v[140:141], v[170:171]
	v_lshlrev_b32_e32 v170, 16, v181
	v_and_b32_e32 v171, 0xffff0000, v181
	v_pk_add_f32 v[138:139], v[138:139], v[170:171]
	s_waitcnt lgkmcnt(0)
	v_lshlrev_b32_e32 v170, 16, v182
	v_and_b32_e32 v171, 0xffff0000, v182
	v_pk_add_f32 v[136:137], v[136:137], v[170:171]
	v_lshlrev_b32_e32 v170, 16, v183
	v_and_b32_e32 v171, 0xffff0000, v183
	v_pk_add_f32 v[134:135], v[134:135], v[170:171]
	v_lshlrev_b32_e32 v170, 16, v184
	v_and_b32_e32 v171, 0xffff0000, v184
	v_pk_add_f32 v[132:133], v[132:133], v[170:171]
	v_lshlrev_b32_e32 v170, 16, v185
	v_and_b32_e32 v171, 0xffff0000, v185
	v_pk_add_f32 v[160:161], v[160:161], v[186:187]
	v_pk_add_f32 v[130:131], v[130:131], v[170:171]
	v_add_u32_e32 v169, 0xfffffef0, v169
	s_cmp_lg_u32 s8, 0
	s_cbranch_scc1 .LBB0_1268
	v_readlane_b32 s8, v253, 39
	v_add3_u32 v182, 0, v166, v167
	s_mov_b64 s[10:11], 0x11101000
	v_add_u32_e32 v168, s8, v168
	v_readlane_b32 s8, v253, 27
	s_mov_b32 s72, 0
	s_nop 0
	v_min_i32_e32 v168, s8, v168
	v_cvt_f32_i32_e32 v170, v168
	ds_read_b128 v[166:169], v182 offset:4080
	v_div_scale_f32 v171, s[8:9], v170, v170, 1.0
	v_rcp_f32_e32 v172, v171
	v_div_scale_f32 v173, vcc, 1.0, v170, 1.0
	s_waitcnt lgkmcnt(0)
	v_lshlrev_b32_e32 v184, 16, v166
	v_fma_f32 v174, -v171, v172, 1.0
	v_fmac_f32_e32 v172, v174, v172
	v_mul_f32_e32 v174, v173, v172
	v_fma_f32 v175, -v171, v174, v173
	v_fmac_f32_e32 v174, v175, v172
	v_fma_f32 v171, -v171, v174, v173
	v_div_fmas_f32 v171, v171, v172, v174
	v_div_fixup_f32 v183, v171, v170, 1.0
	v_fma_f32 v160, v183, v160, -v184
	v_and_b32_e32 v166, 0xffff0000, v166
	v_fma_f32 v161, v183, v161, -v166
	v_cvt_pk_bf16_f32 v166, v160, v161
	v_lshlrev_b32_e32 v160, 16, v167
	v_fma_f32 v158, v183, v158, -v160
	v_and_b32_e32 v160, 0xffff0000, v167
	v_fma_f32 v159, v183, v159, -v160
	v_cvt_pk_bf16_f32 v167, v158, v159
	v_lshlrev_b32_e32 v158, 16, v168
	ds_read_b128 v[170:173], v182 offset:4096
	ds_read_b128 v[174:177], v182 offset:4112
	ds_read_b128 v[178:181], v182 offset:4128
	v_fma_f32 v156, v183, v156, -v158
	v_and_b32_e32 v158, 0xffff0000, v168
	v_fma_f32 v157, v183, v157, -v158
	v_cvt_pk_bf16_f32 v168, v156, v157
	v_lshlrev_b32_e32 v156, 16, v169
	v_fma_f32 v154, v183, v154, -v156
	v_and_b32_e32 v156, 0xffff0000, v169
	v_fma_f32 v155, v183, v155, -v156
	v_cvt_pk_bf16_f32 v169, v154, v155
	s_waitcnt lgkmcnt(2)
	v_lshlrev_b32_e32 v154, 16, v170
	v_fma_f32 v152, v183, v152, -v154
	v_and_b32_e32 v154, 0xffff0000, v170
	v_fma_f32 v153, v183, v153, -v154
	v_cvt_pk_bf16_f32 v152, v152, v153
	v_lshlrev_b32_e32 v153, 16, v171
	v_fma_f32 v150, v183, v150, -v153
	v_and_b32_e32 v153, 0xffff0000, v171
	v_fma_f32 v151, v183, v151, -v153
	v_cvt_pk_bf16_f32 v153, v150, v151
	v_lshlrev_b32_e32 v150, 16, v172
	v_fma_f32 v148, v183, v148, -v150
	v_and_b32_e32 v150, 0xffff0000, v172
	v_fma_f32 v149, v183, v149, -v150
	v_cvt_pk_bf16_f32 v154, v148, v149
	v_lshlrev_b32_e32 v148, 16, v173
	v_fma_f32 v146, v183, v146, -v148
	v_and_b32_e32 v148, 0xffff0000, v173
	v_fma_f32 v147, v183, v147, -v148
	v_cvt_pk_bf16_f32 v155, v146, v147
	s_waitcnt lgkmcnt(1)
	v_lshlrev_b32_e32 v146, 16, v174
	v_fma_f32 v144, v183, v144, -v146
	v_and_b32_e32 v146, 0xffff0000, v174
	v_fma_f32 v145, v183, v145, -v146
	v_cvt_pk_bf16_f32 v144, v144, v145
	v_lshlrev_b32_e32 v145, 16, v175
	v_fma_f32 v142, v183, v142, -v145
	v_and_b32_e32 v145, 0xffff0000, v175
	v_fma_f32 v143, v183, v143, -v145
	v_cvt_pk_bf16_f32 v145, v142, v143
	v_lshlrev_b32_e32 v142, 16, v176
	v_fma_f32 v140, v183, v140, -v142
	v_and_b32_e32 v142, 0xffff0000, v176
	v_fma_f32 v141, v183, v141, -v142
	v_cvt_pk_bf16_f32 v146, v140, v141
	v_lshlrev_b32_e32 v140, 16, v177
	v_fma_f32 v138, v183, v138, -v140
	v_and_b32_e32 v140, 0xffff0000, v177
	v_fma_f32 v139, v183, v139, -v140
	v_cvt_pk_bf16_f32 v147, v138, v139
	s_waitcnt lgkmcnt(0)
	v_lshlrev_b32_e32 v138, 16, v178
	v_fma_f32 v136, v183, v136, -v138
	v_and_b32_e32 v138, 0xffff0000, v178
	v_fma_f32 v137, v183, v137, -v138
	v_cvt_pk_bf16_f32 v136, v136, v137
	v_lshlrev_b32_e32 v137, 16, v179
	v_fma_f32 v134, v183, v134, -v137
	v_and_b32_e32 v137, 0xffff0000, v179
	v_fma_f32 v135, v183, v135, -v137
	v_cvt_pk_bf16_f32 v137, v134, v135
	v_lshlrev_b32_e32 v134, 16, v180
	v_fma_f32 v132, v183, v132, -v134
	v_and_b32_e32 v134, 0xffff0000, v180
	v_fma_f32 v133, v183, v133, -v134
	v_cvt_pk_bf16_f32 v138, v132, v133
	v_lshlrev_b32_e32 v132, 16, v181
	v_fma_f32 v130, v183, v130, -v132
	v_and_b32_e32 v132, 0xffff0000, v181
	s_ashr_i32 s8, s15, 2
	v_fma_f32 v131, v183, v131, -v132
	v_and_or_b32 v142, s8, -16, v165
	v_cvt_pk_bf16_f32 v139, v130, v131
	v_mul_lo_u32 v130, v142, s33
	v_and_b32_e32 v131, 48, v164
	v_add3_u32 v143, 0, v130, v131
	ds_write_b128 v182, v[166:169] offset:40960
	ds_write_b128 v182, v[152:155] offset:40976
	ds_write_b128 v182, v[144:147] offset:40992
	ds_write_b128 v182, v[136:139] offset:41008
	s_waitcnt lgkmcnt(0)
	s_barrier
	ds_read_b128 v[134:137], v143 offset:40960
	ds_read_b128 v[130:133], v143 offset:41024
	s_waitcnt vmcnt(31) lgkmcnt(1)
	v_mfma_f32_16x16x32_bf16 v[114:117], v[114:117], v[134:137], 0
	v_readlane_b32 s8, v253, 32
	s_waitcnt vmcnt(30) lgkmcnt(0)
	v_mfma_f32_16x16x32_bf16 v[138:141], v[110:113], v[130:133], v[114:117]
	s_nop 4
	ds_read_b128 v[114:117], v143 offset:41088
	ds_read_b128 v[110:113], v143 offset:41152
	s_waitcnt vmcnt(29) lgkmcnt(1)
	v_mfma_f32_16x16x32_bf16 v[106:109], v[106:109], v[114:117], v[138:141]
	s_waitcnt vmcnt(28) lgkmcnt(0)
	v_mfma_f32_16x16x32_bf16 v[102:105], v[102:105], v[110:113], v[106:109]
	s_waitcnt vmcnt(1)
	v_mfma_f32_16x16x32_bf16 v[106:109], v[126:129], v[134:137], 0
	v_add_u32_e32 v126, s8, v142
	v_mfma_f32_16x16x32_bf16 v[106:109], v[122:125], v[130:133], v[106:109]
	v_mov_b64_e32 v[122:123], s[24:25]
	v_mad_i64_i32 v[122:123], s[8:9], v126, s70, v[122:123]
	v_mfma_f32_16x16x32_bf16 v[106:109], v[118:121], v[114:117], v[106:109]
	v_readlane_b32 s8, v253, 29
	s_lshl_b32 s28, s8, 1
	v_lshl_add_u64 v[122:123], v[122:123], 0, s[28:29]
	v_mfma_f32_16x16x32_bf16 v[118:121], v[98:101], v[134:137], 0
	v_lshlrev_b32_e32 v124, 3, v163
	v_mov_b32_e32 v125, v33
	v_lshl_add_u64 v[100:101], v[122:123], 0, v[124:125]
	v_mfma_f32_16x16x32_bf16 v[94:97], v[94:97], v[130:133], v[118:121]
	s_mov_b32 s9, 0x11101000
	v_lshl_add_u64 v[98:99], v[100:101], 0, s[10:11]
	v_add_co_u32_e32 v100, vcc, s9, v100
	v_mfma_f32_16x16x32_bf16 v[90:93], v[90:93], v[114:117], v[94:97]
	s_lshl_b32 s8, s8, 2
	v_addc_co_u32_e32 v101, vcc, 0, v101, vcc
	v_mfma_f32_16x16x32_bf16 v[94:97], v[82:85], v[134:137], 0
	s_add_u32 s10, s2, s8
	global_load_dwordx2 v[118:119], v[98:99], off offset:32
	global_load_dwordx2 v[120:121], v[98:99], off offset:64
	global_load_dwordx2 v[122:123], v[98:99], off offset:96
	global_load_dwordx2 v[124:125], v[98:99], off offset:128
	global_load_dwordx2 v[84:85], v[100:101], off
	global_load_dwordx2 v[126:127], v[98:99], off offset:160
	global_load_dwordx2 v[128:129], v[98:99], off offset:192
	global_load_dwordx2 v[82:83], v[98:99], off offset:224
	v_mfma_f32_16x16x32_bf16 v[78:81], v[78:81], v[130:133], v[94:97]
	s_addc_u32 s11, s14, 0
	s_lshl_b32 s8, s18, 11
	v_mfma_f32_16x16x32_bf16 v[74:77], v[74:77], v[114:117], v[78:81]
	s_mov_b32 s2, 0
	s_waitcnt vmcnt(3)
	v_lshlrev_b32_e32 v94, 16, v84
	s_nop 1
	global_load_dwordx4 v[78:81], v32, s[10:11]
	v_mfma_f32_16x16x32_bf16 v[70:73], v[70:73], v[134:137], 0
	s_waitcnt vmcnt(0)
	v_mul_f32_e32 v78, v102, v78
	v_mfma_f32_16x16x32_bf16 v[66:69], v[66:69], v[130:133], v[70:73]
	v_mul_f32_e32 v78, v78, v94
	v_mfma_f32_16x16x32_bf16 v[58:61], v[58:61], v[114:117], v[66:69]
	s_nop 2
	v_mul_f32_e32 v70, v103, v79
	v_and_b32_e32 v71, 0xffff0000, v84
	v_mul_f32_e32 v70, v70, v71
	v_mfma_f32_16x16x32_bf16 v[66:69], v[86:89], v[134:137], 0
	v_mul_f32_e32 v71, v104, v80
	v_lshlrev_b32_e32 v72, 16, v85
	v_mul_f32_e32 v71, v71, v72
	v_mfma_f32_16x16x32_bf16 v[62:65], v[62:65], v[130:133], v[66:69]
	v_mul_f32_e32 v72, v105, v81
	v_and_b32_e32 v73, 0xffff0000, v85
	v_cvt_pk_bf16_f32 v70, v78, v70
	v_mfma_f32_16x16x32_bf16 v[50:53], v[50:53], v[114:117], v[62:65]
	s_nop 0
	v_mul_f32_e32 v66, v72, v73
	v_cvt_pk_bf16_f32 v71, v71, v66
	global_store_dwordx2 v[100:101], v[70:71], off
	v_mfma_f32_16x16x32_bf16 v[38:41], v[38:41], v[110:113], v[106:109]
	s_nop 0
	global_load_dwordx4 v[62:65], v32, s[10:11] offset:64
	v_lshlrev_b32_e32 v66, 16, v118
	v_and_b32_e32 v67, 0xffff0000, v118
	v_mfma_f32_16x16x32_bf16 v[54:57], v[54:57], v[134:137], 0
	v_mfma_f32_16x16x32_bf16 v[20:23], v[20:23], v[110:113], v[90:93]
	s_waitcnt vmcnt(0)
	s_nop 0
	v_mul_f32_e32 v38, v38, v62
	v_mul_f32_e32 v39, v39, v63
	v_mul_f32_e32 v38, v38, v66
	v_mul_f32_e32 v40, v40, v64
	v_mul_f32_e32 v39, v39, v67
	v_cvt_pk_bf16_f32 v62, v38, v39
	v_lshlrev_b32_e32 v38, 16, v119
	v_mul_f32_e32 v63, v40, v38
	v_mul_f32_e32 v64, v41, v65
	v_mfma_f32_16x16x32_bf16 v[38:41], v[46:49], v[130:133], v[54:57]
	v_and_b32_e32 v65, 0xffff0000, v119
	v_mul_f32_e32 v46, v64, v65
	v_cvt_pk_bf16_f32 v63, v63, v46
	global_store_dwordx2 v[98:99], v[62:63], off offset:32
	v_mfma_f32_16x16x32_bf16 v[38:41], v[42:45], v[114:117], v[38:41]
	global_load_dwordx4 v[42:45], v32, s[10:11] offset:128
	v_lshlrev_b32_e32 v46, 16, v120
	v_and_b32_e32 v47, 0xffff0000, v120
	v_lshlrev_b32_e32 v48, 16, v121
	v_and_b32_e32 v49, 0xffff0000, v121
	v_mfma_f32_16x16x32_bf16 v[16:19], v[16:19], v[110:113], v[74:77]
	s_waitcnt vmcnt(0)
	v_mul_f32_e32 v20, v20, v42
	v_mul_f32_e32 v21, v21, v43
	v_mul_f32_e32 v22, v22, v44
	v_mul_f32_e32 v23, v23, v45
	v_mul_f32_e32 v20, v20, v46
	v_mul_f32_e32 v21, v21, v47
	v_mul_f32_e32 v22, v22, v48
	v_mul_f32_e32 v23, v23, v49
	v_cvt_pk_bf16_f32 v20, v20, v21
	v_cvt_pk_bf16_f32 v21, v22, v23
	global_store_dwordx2 v[98:99], v[20:21], off offset:64
	global_load_dwordx4 v[20:23], v32, s[10:11] offset:192
	v_lshlrev_b32_e32 v42, 16, v122
	v_and_b32_e32 v43, 0xffff0000, v122
	v_lshlrev_b32_e32 v44, 16, v123
	v_and_b32_e32 v45, 0xffff0000, v123
	v_mfma_f32_16x16x32_bf16 v[8:11], v[8:11], v[134:137], 0
	s_waitcnt vmcnt(0)
	v_mul_f32_e32 v16, v16, v20
	v_mul_f32_e32 v17, v17, v21
	v_mul_f32_e32 v18, v18, v22
	v_mul_f32_e32 v19, v19, v23
	v_mul_f32_e32 v16, v16, v42
	v_mul_f32_e32 v17, v17, v43
	v_mul_f32_e32 v18, v18, v44
	v_mul_f32_e32 v19, v19, v45
	v_cvt_pk_bf16_f32 v16, v16, v17
	v_cvt_pk_bf16_f32 v17, v18, v19
	global_store_dwordx2 v[98:99], v[16:17], off offset:96
	global_load_dwordx4 v[16:19], v32, s[10:11] offset:256
	v_mfma_f32_16x16x32_bf16 v[20:23], v[34:37], v[110:113], v[58:61]
	v_lshlrev_b32_e32 v34, 16, v124
	v_and_b32_e32 v35, 0xffff0000, v124
	v_lshlrev_b32_e32 v36, 16, v125
	v_and_b32_e32 v37, 0xffff0000, v125
	v_mfma_f32_16x16x32_bf16 v[4:7], v[4:7], v[130:133], v[8:11]
	s_waitcnt vmcnt(0)
	s_nop 1
	v_mul_f32_e32 v16, v20, v16
	v_mul_f32_e32 v17, v21, v17
	v_mul_f32_e32 v18, v22, v18
	v_mul_f32_e32 v19, v23, v19
	v_mul_f32_e32 v16, v16, v34
	v_mul_f32_e32 v17, v17, v35
	v_mul_f32_e32 v18, v18, v36
	v_mul_f32_e32 v19, v19, v37
	v_cvt_pk_bf16_f32 v16, v16, v17
	v_cvt_pk_bf16_f32 v17, v18, v19
	global_store_dwordx2 v[98:99], v[16:17], off offset:128
	global_load_dwordx4 v[16:19], v32, s[10:11] offset:320
	v_mfma_f32_16x16x32_bf16 v[20:23], v[28:31], v[110:113], v[50:53]
	v_lshlrev_b32_e32 v28, 16, v126
	v_and_b32_e32 v29, 0xffff0000, v126
	v_lshlrev_b32_e32 v30, 16, v127
	v_and_b32_e32 v31, 0xffff0000, v127
	v_mfma_f32_16x16x32_bf16 v[0:3], v[0:3], v[114:117], v[4:7]
	s_waitcnt vmcnt(0)
	s_nop 1
	v_mul_f32_e32 v16, v20, v16
	v_mul_f32_e32 v17, v21, v17
	v_mul_f32_e32 v18, v22, v18
	v_mul_f32_e32 v19, v23, v19
	v_mul_f32_e32 v16, v16, v28
	v_mul_f32_e32 v17, v17, v29
	v_mul_f32_e32 v18, v18, v30
	v_mul_f32_e32 v19, v19, v31
	v_cvt_pk_bf16_f32 v16, v16, v17
	v_cvt_pk_bf16_f32 v17, v18, v19
	global_store_dwordx2 v[98:99], v[16:17], off offset:160
	global_load_dwordx4 v[16:19], v32, s[10:11] offset:384
	v_mfma_f32_16x16x32_bf16 v[20:23], v[24:27], v[110:113], v[38:41]
	v_lshlrev_b32_e32 v24, 16, v128
	v_and_b32_e32 v25, 0xffff0000, v128
	v_lshlrev_b32_e32 v26, 16, v129
	v_and_b32_e32 v27, 0xffff0000, v129
	v_mfma_f32_16x16x32_bf16 v[0:3], v[12:15], v[110:113], v[0:3]
	v_lshlrev_b32_e32 v4, 16, v82
	v_and_b32_e32 v5, 0xffff0000, v82
	v_lshlrev_b32_e32 v6, 16, v83
	v_and_b32_e32 v7, 0xffff0000, v83
	s_waitcnt vmcnt(0)
	v_mul_f32_e32 v16, v20, v16
	v_mul_f32_e32 v17, v21, v17
	v_mul_f32_e32 v18, v22, v18
	v_mul_f32_e32 v19, v23, v19
	v_mul_f32_e32 v16, v16, v24
	v_mul_f32_e32 v17, v17, v25
	v_mul_f32_e32 v18, v18, v26
	v_mul_f32_e32 v19, v19, v27
	v_cvt_pk_bf16_f32 v16, v16, v17
	v_cvt_pk_bf16_f32 v17, v18, v19
	global_store_dwordx2 v[98:99], v[16:17], off offset:192
	global_load_dwordx4 v[16:19], v32, s[10:11] offset:448
	v_xor_b32_e32 v20, 16, v226
	v_xor_b32_e32 v21, 32, v226
	v_cmp_lt_i32_e32 vcc, v20, v162
	v_readlane_b32 s10, v251, 33
	v_readlane_b32 s11, v251, 34
	v_cndmask_b32_e32 v20, v226, v20, vcc
	v_cmp_lt_i32_e32 vcc, v21, v162
	s_add_u32 s66, s10, s8
	v_lshlrev_b32_e32 v100, 2, v20
	v_cndmask_b32_e32 v8, v226, v21, vcc
	v_lshlrev_b32_e32 v101, 2, v8
	s_addc_u32 s67, s11, 0
	s_waitcnt vmcnt(0)
	v_mul_f32_e32 v0, v0, v16
	v_mul_f32_e32 v1, v1, v17
	v_mul_f32_e32 v2, v2, v18
	v_mul_f32_e32 v3, v3, v19
	v_mul_f32_e32 v0, v0, v4
	v_mul_f32_e32 v1, v1, v5
	v_mul_f32_e32 v2, v2, v6
	v_mul_f32_e32 v3, v3, v7
	v_cvt_pk_bf16_f32 v0, v0, v1
	v_cvt_pk_bf16_f32 v1, v2, v3
	global_store_dwordx2 v[98:99], v[0:1], off offset:224
	s_barrier
	s_mov_b32 s48, 2
	s_branch .Lpf_issue

.LBB0_1270:
	s_or_b64 exec, exec, s[10:11]
	s_waitcnt vmcnt(0)
	s_barrier
	v_readlane_b32 s50, v252, 56
	v_readlane_b32 s51, v252, 55
	v_readlane_b32 s52, v253, 22
	v_and_b32_e32 v102, 15, v218
	v_lshlrev_b32_e32 v102, 4, v102
	v_lshrrev_b32_e32 v103, 4, v218
	s_and_b32 s53, s72, 1
	s_lshl_b32 s53, s53, 1
	s_or_b32 s50, s50, s53
	s_lshr_b32 s51, s51, 2
	s_lshl_b32 s54, s50, 12
	s_lshl_b32 s55, s51, 7
	s_add_u32 s54, s54, s55
	s_lshl_b32 s55, s54, 10
	s_lshl_b32 s56, s52, 8
	s_add_u32 s55, s55, s56
	s_add_u32 s55, s55, 0xa100000
	s_add_u32 s58, s24, s55
	s_addc_u32 s59, s25, 0
	s_add_u32 s60, s58, 0x1000000
	s_addc_u32 s61, s59, 0
	s_add_u32 s62, s58, 0x2000000
	s_addc_u32 s63, s59, 0
	s_mul_i32 s55, s54, 0x5400
	s_add_u32 s55, s55, s56
	s_add_u32 s55, s55, 0x11102800
	s_add_u32 s56, s24, s55
	s_addc_u32 s57, s25, 0
	s_lshl_b32 s53, s50, 5
	s_add_u32 s53, s53, s51
	s_lshl_b32 s53, s53, 2
	s_add_u32 s53, s53, s52
	s_lshl_b32 s53, s53, 7
	s_lshl_b32 s54, s50, 7
	s_add_u32 s54, s54, s52
	s_lshr_b32 s55, s51, 2
	s_lshl_b32 s55, s55, 2
	s_add_u32 s55, s54, s55
	s_lshl_b32 s55, s55, 7
	s_and_b32 s49, s51, 3
	s_lshl_b32 s49, s49, 5
	s_add_u32 s55, s55, s49
	s_add_u32 s55, s55, 0x10000
	s_lshr_b32 s49, s51, 4
	s_lshl_b32 s49, s49, 2
	s_add_u32 s54, s54, s49
	s_lshl_b32 s54, s54, 7
	s_and_b32 s49, s51, 15
	s_lshl_b32 s49, s49, 3
	s_add_u32 s54, s54, s49
	s_add_u32 s54, s54, 0x20000
	v_lshl_add_u32 v116, v103, 10, v102
	v_add_u32_e32 v117, 0x8000, v116
	v_add_u32_e32 v118, 0x10000, v116
	v_add_u32_e32 v119, 0x18000, v116
	v_mul_u32_u24_e32 v120, 0x5400, v103
	v_add_u32_e32 v120, v120, v102
	v_add_u32_e32 v121, 0xa8000, v120
	v_add_u32_e32 v122, 0x150000, v120
	v_add_u32_e32 v123, 0x1f8000, v120
	v_add_u32_e32 v124, s53, v103
	v_lshlrev_b32_e32 v124, 2, v124
	v_and_b32_e32 v125, 3, v103
	v_lshrrev_b32_e32 v126, 2, v103
	v_lshl_add_u32 v125, v125, 12, v126
	v_add_u32_e32 v125, s55, v125
	v_lshlrev_b32_e32 v125, 2, v125
	v_and_b32_e32 v126, 15, v103
	v_lshrrev_b32_e32 v127, 4, v103
	v_lshl_add_u32 v126, v126, 10, v127
	v_add_u32_e32 v126, s54, v126
	v_lshlrev_b32_e32 v126, 2, v126
	global_load_dword v104, v124, s[68:69]
	global_load_dword v105, v125, s[68:69]
	global_load_dword v106, v126, s[68:69]
	global_load_dword v107, v124, s[68:69] offset:128
	global_load_dword v108, v125, s[68:69] offset:32
	global_load_dword v109, v126, s[68:69] offset:8
	global_load_dword v110, v124, s[68:69] offset:256
	global_load_dword v111, v125, s[68:69] offset:64
	global_load_dword v112, v126, s[68:69] offset:16
	global_load_dword v113, v124, s[68:69] offset:384
	global_load_dword v114, v125, s[68:69] offset:96
	global_load_dword v115, v126, s[68:69] offset:24
	global_load_dwordx4 v[0:3], v116, s[58:59]
	global_load_dwordx4 v[4:7], v116, s[60:61]
	global_load_dwordx4 v[8:11], v116, s[62:63]
	global_load_dwordx4 v[12:15], v120, s[56:57]
	global_load_dwordx4 v[16:19], v117, s[58:59]
	global_load_dwordx4 v[20:23], v117, s[60:61]
	global_load_dwordx4 v[24:27], v117, s[62:63]
	global_load_dwordx4 v[28:31], v121, s[56:57]
	global_load_dwordx4 v[34:37], v118, s[58:59]
	global_load_dwordx4 v[38:41], v118, s[60:61]
	global_load_dwordx4 v[42:45], v118, s[62:63]
	global_load_dwordx4 v[46:49], v122, s[56:57]
	global_load_dwordx4 v[50:53], v119, s[58:59]
	global_load_dwordx4 v[54:57], v119, s[60:61]
	global_load_dwordx4 v[58:61], v119, s[62:63]
	global_load_dwordx4 v[62:65], v123, s[56:57]
	s_waitcnt vmcnt(0)
	v_max3_f32 v144, v104, v105, v106
	v_sub_f32_e32 v104, v104, v144
	v_sub_f32_e32 v105, v105, v144
	v_sub_f32_e32 v106, v106, v144
	v_exp_f32_e32 v104, v104
	v_exp_f32_e32 v105, v105
	v_exp_f32_e32 v106, v106
	s_nop 0
	v_add_f32_e32 v144, v104, v105
	v_add_f32_e32 v144, v106, v144
	v_rcp_f32_e32 v144, v144
	s_nop 0
	v_mul_f32_e32 v104, v104, v144
	v_mul_f32_e32 v105, v105, v144
	v_mul_f32_e32 v106, v106, v144
	v_lshlrev_b32_e32 v145, 16, v0
	v_lshlrev_b32_e32 v146, 16, v4
	v_lshlrev_b32_e32 v147, 16, v8
	v_lshlrev_b32_e32 v148, 16, v12
	v_mul_f32_e32 v145, v104, v145
	v_fmac_f32_e32 v145, v105, v146
	v_fmac_f32_e32 v145, v106, v147
	v_mul_f32_e32 v145, v145, v148
	v_and_b32_e32 v149, 0xffff0000, v0
	v_and_b32_e32 v150, 0xffff0000, v4
	v_and_b32_e32 v151, 0xffff0000, v8
	v_and_b32_e32 v152, 0xffff0000, v12
	v_mul_f32_e32 v149, v104, v149
	v_fmac_f32_e32 v149, v105, v150
	v_fmac_f32_e32 v149, v106, v151
	v_mul_f32_e32 v149, v149, v152
	v_cvt_pk_bf16_f32 v0, v145, v149
	v_lshlrev_b32_e32 v145, 16, v1
	v_lshlrev_b32_e32 v146, 16, v5
	v_lshlrev_b32_e32 v147, 16, v9
	v_lshlrev_b32_e32 v148, 16, v13
	v_mul_f32_e32 v145, v104, v145
	v_fmac_f32_e32 v145, v105, v146
	v_fmac_f32_e32 v145, v106, v147
	v_mul_f32_e32 v145, v145, v148
	v_and_b32_e32 v149, 0xffff0000, v1
	v_and_b32_e32 v150, 0xffff0000, v5
	v_and_b32_e32 v151, 0xffff0000, v9
	v_and_b32_e32 v152, 0xffff0000, v13
	v_mul_f32_e32 v149, v104, v149
	v_fmac_f32_e32 v149, v105, v150
	v_fmac_f32_e32 v149, v106, v151
	v_mul_f32_e32 v149, v149, v152
	v_cvt_pk_bf16_f32 v1, v145, v149
	v_lshlrev_b32_e32 v145, 16, v2
	v_lshlrev_b32_e32 v146, 16, v6
	v_lshlrev_b32_e32 v147, 16, v10
	v_lshlrev_b32_e32 v148, 16, v14
	v_mul_f32_e32 v145, v104, v145
	v_fmac_f32_e32 v145, v105, v146
	v_fmac_f32_e32 v145, v106, v147
	v_mul_f32_e32 v145, v145, v148
	v_and_b32_e32 v149, 0xffff0000, v2
	v_and_b32_e32 v150, 0xffff0000, v6
	v_and_b32_e32 v151, 0xffff0000, v10
	v_and_b32_e32 v152, 0xffff0000, v14
	v_mul_f32_e32 v149, v104, v149
	v_fmac_f32_e32 v149, v105, v150
	v_fmac_f32_e32 v149, v106, v151
	v_mul_f32_e32 v149, v149, v152
	v_cvt_pk_bf16_f32 v2, v145, v149
	v_lshlrev_b32_e32 v145, 16, v3
	v_lshlrev_b32_e32 v146, 16, v7
	v_lshlrev_b32_e32 v147, 16, v11
	v_lshlrev_b32_e32 v148, 16, v15
	v_mul_f32_e32 v145, v104, v145
	v_fmac_f32_e32 v145, v105, v146
	v_fmac_f32_e32 v145, v106, v147
	v_mul_f32_e32 v145, v145, v148
	v_and_b32_e32 v149, 0xffff0000, v3
	v_and_b32_e32 v150, 0xffff0000, v7
	v_and_b32_e32 v151, 0xffff0000, v11
	v_and_b32_e32 v152, 0xffff0000, v15
	v_mul_f32_e32 v149, v104, v149
	v_fmac_f32_e32 v149, v105, v150
	v_fmac_f32_e32 v149, v106, v151
	v_mul_f32_e32 v149, v149, v152
	v_cvt_pk_bf16_f32 v3, v145, v149
	global_store_dwordx4 v120, v[0:3], s[56:57]
	v_max3_f32 v144, v107, v108, v109
	v_sub_f32_e32 v107, v107, v144
	v_sub_f32_e32 v108, v108, v144
	v_sub_f32_e32 v109, v109, v144
	v_exp_f32_e32 v107, v107
	v_exp_f32_e32 v108, v108
	v_exp_f32_e32 v109, v109
	s_nop 0
	v_add_f32_e32 v144, v107, v108
	v_add_f32_e32 v144, v109, v144
	v_rcp_f32_e32 v144, v144
	s_nop 0
	v_mul_f32_e32 v107, v107, v144
	v_mul_f32_e32 v108, v108, v144
	v_mul_f32_e32 v109, v109, v144
	v_lshlrev_b32_e32 v145, 16, v16
	v_lshlrev_b32_e32 v146, 16, v20
	v_lshlrev_b32_e32 v147, 16, v24
	v_lshlrev_b32_e32 v148, 16, v28
	v_mul_f32_e32 v145, v107, v145
	v_fmac_f32_e32 v145, v108, v146
	v_fmac_f32_e32 v145, v109, v147
	v_mul_f32_e32 v145, v145, v148
	v_and_b32_e32 v149, 0xffff0000, v16
	v_and_b32_e32 v150, 0xffff0000, v20
	v_and_b32_e32 v151, 0xffff0000, v24
	v_and_b32_e32 v152, 0xffff0000, v28
	v_mul_f32_e32 v149, v107, v149
	v_fmac_f32_e32 v149, v108, v150
	v_fmac_f32_e32 v149, v109, v151
	v_mul_f32_e32 v149, v149, v152
	v_cvt_pk_bf16_f32 v16, v145, v149
	v_lshlrev_b32_e32 v145, 16, v17
	v_lshlrev_b32_e32 v146, 16, v21
	v_lshlrev_b32_e32 v147, 16, v25
	v_lshlrev_b32_e32 v148, 16, v29
	v_mul_f32_e32 v145, v107, v145
	v_fmac_f32_e32 v145, v108, v146
	v_fmac_f32_e32 v145, v109, v147
	v_mul_f32_e32 v145, v145, v148
	v_and_b32_e32 v149, 0xffff0000, v17
	v_and_b32_e32 v150, 0xffff0000, v21
	v_and_b32_e32 v151, 0xffff0000, v25
	v_and_b32_e32 v152, 0xffff0000, v29
	v_mul_f32_e32 v149, v107, v149
	v_fmac_f32_e32 v149, v108, v150
	v_fmac_f32_e32 v149, v109, v151
	v_mul_f32_e32 v149, v149, v152
	v_cvt_pk_bf16_f32 v17, v145, v149
	v_lshlrev_b32_e32 v145, 16, v18
	v_lshlrev_b32_e32 v146, 16, v22
	v_lshlrev_b32_e32 v147, 16, v26
	v_lshlrev_b32_e32 v148, 16, v30
	v_mul_f32_e32 v145, v107, v145
	v_fmac_f32_e32 v145, v108, v146
	v_fmac_f32_e32 v145, v109, v147
	v_mul_f32_e32 v145, v145, v148
	v_and_b32_e32 v149, 0xffff0000, v18
	v_and_b32_e32 v150, 0xffff0000, v22
	v_and_b32_e32 v151, 0xffff0000, v26
	v_and_b32_e32 v152, 0xffff0000, v30
	v_mul_f32_e32 v149, v107, v149
	v_fmac_f32_e32 v149, v108, v150
	v_fmac_f32_e32 v149, v109, v151
	v_mul_f32_e32 v149, v149, v152
	v_cvt_pk_bf16_f32 v18, v145, v149
	v_lshlrev_b32_e32 v145, 16, v19
	v_lshlrev_b32_e32 v146, 16, v23
	v_lshlrev_b32_e32 v147, 16, v27
	v_lshlrev_b32_e32 v148, 16, v31
	v_mul_f32_e32 v145, v107, v145
	v_fmac_f32_e32 v145, v108, v146
	v_fmac_f32_e32 v145, v109, v147
	v_mul_f32_e32 v145, v145, v148
	v_and_b32_e32 v149, 0xffff0000, v19
	v_and_b32_e32 v150, 0xffff0000, v23
	v_and_b32_e32 v151, 0xffff0000, v27
	v_and_b32_e32 v152, 0xffff0000, v31
	v_mul_f32_e32 v149, v107, v149
	v_fmac_f32_e32 v149, v108, v150
	v_fmac_f32_e32 v149, v109, v151
	v_mul_f32_e32 v149, v149, v152
	v_cvt_pk_bf16_f32 v19, v145, v149
	global_store_dwordx4 v121, v[16:19], s[56:57]
	v_max3_f32 v144, v110, v111, v112
	v_sub_f32_e32 v110, v110, v144
	v_sub_f32_e32 v111, v111, v144
	v_sub_f32_e32 v112, v112, v144
	v_exp_f32_e32 v110, v110
	v_exp_f32_e32 v111, v111
	v_exp_f32_e32 v112, v112
	s_nop 0
	v_add_f32_e32 v144, v110, v111
	v_add_f32_e32 v144, v112, v144
	v_rcp_f32_e32 v144, v144
	s_nop 0
	v_mul_f32_e32 v110, v110, v144
	v_mul_f32_e32 v111, v111, v144
	v_mul_f32_e32 v112, v112, v144
	v_lshlrev_b32_e32 v145, 16, v34
	v_lshlrev_b32_e32 v146, 16, v38
	v_lshlrev_b32_e32 v147, 16, v42
	v_lshlrev_b32_e32 v148, 16, v46
	v_mul_f32_e32 v145, v110, v145
	v_fmac_f32_e32 v145, v111, v146
	v_fmac_f32_e32 v145, v112, v147
	v_mul_f32_e32 v145, v145, v148
	v_and_b32_e32 v149, 0xffff0000, v34
	v_and_b32_e32 v150, 0xffff0000, v38
	v_and_b32_e32 v151, 0xffff0000, v42
	v_and_b32_e32 v152, 0xffff0000, v46
	v_mul_f32_e32 v149, v110, v149
	v_fmac_f32_e32 v149, v111, v150
	v_fmac_f32_e32 v149, v112, v151
	v_mul_f32_e32 v149, v149, v152
	v_cvt_pk_bf16_f32 v34, v145, v149
	v_lshlrev_b32_e32 v145, 16, v35
	v_lshlrev_b32_e32 v146, 16, v39
	v_lshlrev_b32_e32 v147, 16, v43
	v_lshlrev_b32_e32 v148, 16, v47
	v_mul_f32_e32 v145, v110, v145
	v_fmac_f32_e32 v145, v111, v146
	v_fmac_f32_e32 v145, v112, v147
	v_mul_f32_e32 v145, v145, v148
	v_and_b32_e32 v149, 0xffff0000, v35
	v_and_b32_e32 v150, 0xffff0000, v39
	v_and_b32_e32 v151, 0xffff0000, v43
	v_and_b32_e32 v152, 0xffff0000, v47
	v_mul_f32_e32 v149, v110, v149
	v_fmac_f32_e32 v149, v111, v150
	v_fmac_f32_e32 v149, v112, v151
	v_mul_f32_e32 v149, v149, v152
	v_cvt_pk_bf16_f32 v35, v145, v149
	v_lshlrev_b32_e32 v145, 16, v36
	v_lshlrev_b32_e32 v146, 16, v40
	v_lshlrev_b32_e32 v147, 16, v44
	v_lshlrev_b32_e32 v148, 16, v48
	v_mul_f32_e32 v145, v110, v145
	v_fmac_f32_e32 v145, v111, v146
	v_fmac_f32_e32 v145, v112, v147
	v_mul_f32_e32 v145, v145, v148
	v_and_b32_e32 v149, 0xffff0000, v36
	v_and_b32_e32 v150, 0xffff0000, v40
	v_and_b32_e32 v151, 0xffff0000, v44
	v_and_b32_e32 v152, 0xffff0000, v48
	v_mul_f32_e32 v149, v110, v149
	v_fmac_f32_e32 v149, v111, v150
	v_fmac_f32_e32 v149, v112, v151
	v_mul_f32_e32 v149, v149, v152
	v_cvt_pk_bf16_f32 v36, v145, v149
	v_lshlrev_b32_e32 v145, 16, v37
	v_lshlrev_b32_e32 v146, 16, v41
	v_lshlrev_b32_e32 v147, 16, v45
	v_lshlrev_b32_e32 v148, 16, v49
	v_mul_f32_e32 v145, v110, v145
	v_fmac_f32_e32 v145, v111, v146
	v_fmac_f32_e32 v145, v112, v147
	v_mul_f32_e32 v145, v145, v148
	v_and_b32_e32 v149, 0xffff0000, v37
	v_and_b32_e32 v150, 0xffff0000, v41
	v_and_b32_e32 v151, 0xffff0000, v45
	v_and_b32_e32 v152, 0xffff0000, v49
	v_mul_f32_e32 v149, v110, v149
	v_fmac_f32_e32 v149, v111, v150
	v_fmac_f32_e32 v149, v112, v151
	v_mul_f32_e32 v149, v149, v152
	v_cvt_pk_bf16_f32 v37, v145, v149
	global_store_dwordx4 v122, v[34:37], s[56:57]
	v_max3_f32 v144, v113, v114, v115
	v_sub_f32_e32 v113, v113, v144
	v_sub_f32_e32 v114, v114, v144
	v_sub_f32_e32 v115, v115, v144
	v_exp_f32_e32 v113, v113
	v_exp_f32_e32 v114, v114
	v_exp_f32_e32 v115, v115
	s_nop 0
	v_add_f32_e32 v144, v113, v114
	v_add_f32_e32 v144, v115, v144
	v_rcp_f32_e32 v144, v144
	s_nop 0
	v_mul_f32_e32 v113, v113, v144
	v_mul_f32_e32 v114, v114, v144
	v_mul_f32_e32 v115, v115, v144
	v_lshlrev_b32_e32 v145, 16, v50
	v_lshlrev_b32_e32 v146, 16, v54
	v_lshlrev_b32_e32 v147, 16, v58
	v_lshlrev_b32_e32 v148, 16, v62
	v_mul_f32_e32 v145, v113, v145
	v_fmac_f32_e32 v145, v114, v146
	v_fmac_f32_e32 v145, v115, v147
	v_mul_f32_e32 v145, v145, v148
	v_and_b32_e32 v149, 0xffff0000, v50
	v_and_b32_e32 v150, 0xffff0000, v54
	v_and_b32_e32 v151, 0xffff0000, v58
	v_and_b32_e32 v152, 0xffff0000, v62
	v_mul_f32_e32 v149, v113, v149
	v_fmac_f32_e32 v149, v114, v150
	v_fmac_f32_e32 v149, v115, v151
	v_mul_f32_e32 v149, v149, v152
	v_cvt_pk_bf16_f32 v50, v145, v149
	v_lshlrev_b32_e32 v145, 16, v51
	v_lshlrev_b32_e32 v146, 16, v55
	v_lshlrev_b32_e32 v147, 16, v59
	v_lshlrev_b32_e32 v148, 16, v63
	v_mul_f32_e32 v145, v113, v145
	v_fmac_f32_e32 v145, v114, v146
	v_fmac_f32_e32 v145, v115, v147
	v_mul_f32_e32 v145, v145, v148
	v_and_b32_e32 v149, 0xffff0000, v51
	v_and_b32_e32 v150, 0xffff0000, v55
	v_and_b32_e32 v151, 0xffff0000, v59
	v_and_b32_e32 v152, 0xffff0000, v63
	v_mul_f32_e32 v149, v113, v149
	v_fmac_f32_e32 v149, v114, v150
	v_fmac_f32_e32 v149, v115, v151
	v_mul_f32_e32 v149, v149, v152
	v_cvt_pk_bf16_f32 v51, v145, v149
	v_lshlrev_b32_e32 v145, 16, v52
	v_lshlrev_b32_e32 v146, 16, v56
	v_lshlrev_b32_e32 v147, 16, v60
	v_lshlrev_b32_e32 v148, 16, v64
	v_mul_f32_e32 v145, v113, v145
	v_fmac_f32_e32 v145, v114, v146
	v_fmac_f32_e32 v145, v115, v147
	v_mul_f32_e32 v145, v145, v148
	v_and_b32_e32 v149, 0xffff0000, v52
	v_and_b32_e32 v150, 0xffff0000, v56
	v_and_b32_e32 v151, 0xffff0000, v60
	v_and_b32_e32 v152, 0xffff0000, v64
	v_mul_f32_e32 v149, v113, v149
	v_fmac_f32_e32 v149, v114, v150
	v_fmac_f32_e32 v149, v115, v151
	v_mul_f32_e32 v149, v149, v152
	v_cvt_pk_bf16_f32 v52, v145, v149
	v_lshlrev_b32_e32 v145, 16, v53
	v_lshlrev_b32_e32 v146, 16, v57
	v_lshlrev_b32_e32 v147, 16, v61
	v_lshlrev_b32_e32 v148, 16, v65
	v_mul_f32_e32 v145, v113, v145
	v_fmac_f32_e32 v145, v114, v146
	v_fmac_f32_e32 v145, v115, v147
	v_mul_f32_e32 v145, v145, v148
	v_and_b32_e32 v149, 0xffff0000, v53
	v_and_b32_e32 v150, 0xffff0000, v57
	v_and_b32_e32 v151, 0xffff0000, v61
	v_and_b32_e32 v152, 0xffff0000, v65
	v_mul_f32_e32 v149, v113, v149
	v_fmac_f32_e32 v149, v114, v150
	v_fmac_f32_e32 v149, v115, v151
	v_mul_f32_e32 v149, v149, v152
	v_cvt_pk_bf16_f32 v53, v145, v149
	global_store_dwordx4 v123, v[50:53], s[56:57]
.LBB0_1271:
	s_add_i32 s72, s72, 1
	s_add_i32 s2, s2, 2
	s_cmp_eq_u32 s72, 8
	s_cbranch_scc1 .LBB0_1388
	s_cmp_eq_u32 s72, 6
	s_cbranch_scc0 .Lmid_skip
	v_writelane_b32 v255, s2, 8
	s_getreg_b32 s2, hwreg(HW_REG_XCC_ID, 0, 4)
	s_waitcnt vmcnt(0)
	s_barrier
	s_mov_b64 s[10:11], exec
	v_readlane_b32 s8, v251, 2
	v_readlane_b32 s9, v251, 3
	s_and_b64 s[8:9], s[10:11], s[8:9]
	s_mov_b64 exec, s[8:9]
	s_cbranch_execz .LBB0_1441_m
	v_readlane_b32 s8, v254, 54
	s_waitcnt vmcnt(0) expcnt(0) lgkmcnt(0)
	s_and_b32 s2, s2, 15
	v_mov_b32_e32 v0, s8
	ds_read_b32 v2, v0
	v_readlane_b32 s8, v254, 55
	s_waitcnt lgkmcnt(0)
	v_cmp_ne_u32_e32 vcc, 0, v2
	v_mov_b32_e32 v0, s8
	ds_read_b32 v0, v0
	s_cbranch_vccnz .LBB0_1405_m
	s_mov_b32 s8, 1
	s_branch .LBB0_1393_m

.LBB0_1441_m:
	s_or_b64 exec, exec, s[10:11]
	s_waitcnt vmcnt(0) lgkmcnt(0)
	s_barrier
	v_readlane_b32 s2, v255, 8
	s_nop 1
.Lmid_skip:
.LBB0_1272:
	v_lshrrev_b32_e32 v227, 4, v218
	v_and_b32_e32 v244, 15, v218
	v_lshlrev_b32_e32 v244, 4, v244
	v_mul_u32_u24_e32 v245, 0x120, v227
	v_add3_u32 v245, s27, v244, v245
	v_mad_u32_u24 v244, v227, s33, v244
	s_cmp_lg_u32 s72, 0
	s_cbranch_scc1 .Lpf_wait_cnt
	s_waitcnt vmcnt(0)
.Lpf_wait_cnt:
	s_waitcnt vmcnt(8)
	ds_write_b128 v244, v[154:157]
	ds_write_b128 v245, v[158:161]
	ds_write_b128 v244, v[162:165] offset:8704
	ds_write_b128 v245, v[166:169] offset:9216
	ds_write_b128 v244, v[170:173] offset:17408
	ds_write_b128 v245, v[174:177] offset:18432
	ds_write_b128 v244, v[178:181] offset:26112
	ds_write_b128 v245, v[182:185] offset:27648
	ds_write_b128 v244, v[186:189] offset:34816
	ds_write_b128 v245, v[190:193] offset:36864
	ds_write_b128 v244, v[194:197] offset:43520
	ds_write_b128 v245, v[198:201] offset:46080
	ds_write_b128 v244, v[202:205] offset:52224
	ds_write_b128 v245, v[206:209] offset:55296
	ds_write_b128 v244, v[210:213] offset:60928
	ds_write_b128 v245, v[214:217] offset:64512
	s_waitcnt lgkmcnt(0)
	s_barrier
	s_and_b32 s8, s2, 2
	v_readlane_b32 s9, v252, 56
	s_or_b32 s74, s8, s9
	v_mov_b32_e32 v99, v218
	s_lshl_b32 s8, s74, 7
	v_readlane_b32 s9, v252, 55
	s_or_b32 s8, s9, s8
	v_readfirstlane_b32 s76, v99
	v_readlane_b32 s9, v253, 22
	s_ashr_i32 s73, s76, 6
	s_or_b32 s75, s8, s9
	v_and_b32_e32 v98, 63, v99
	s_add_u32 s49, s72, 2
	s_and_b32 s49, s49, 7
	s_cmp_gt_u32 s49, 1
	s_mov_b64 s[10:11], -1
	s_cbranch_scc0 .LBB0_1352
	s_cmp_gt_u32 s49, 3
	s_cbranch_scc0 .LBB0_1314
	s_lshl_b32 s77, s75, 7
	s_and_b32 s12, s77, 0x180
	v_ashrrev_i32_e32 v104, 4, v99
	s_movk_i32 s9, 0x120
	s_cmp_gt_u32 s49, 5
	v_mul_lo_u32 v102, v104, s33
	v_mul_lo_u32 v103, v104, s9
	s_cbranch_scc0 .LBB0_1276
	s_lshl_b32 s10, s8, 5
	s_lshl_b32 s28, s12, 1
	s_add_u32 s8, s66, s28
	v_lshl_add_u32 v0, s74, 8, v104
	v_lshlrev_b32_e32 v1, 4, v99
	s_addc_u32 s9, s67, 0
	v_and_b32_e32 v32, 0xf0, v1
	v_ashrrev_i32_e32 v1, 31, v0
	v_lshl_add_u64 v[2:3], s[8:9], 0, v[32:33]
	v_lshlrev_b64 v[0:1], 13, v[0:1]
	v_lshl_add_u64 v[0:1], v[2:3], 0, v[0:1]
	s_mov_b64 s[8:9], 0x40000
	v_lshl_add_u64 v[2:3], v[0:1], 0, s[8:9]
	s_mov_b32 s8, 0x40000
	v_add_co_u32_e32 v12, vcc, s8, v0
	s_mov_b64 s[8:9], 0x80000
	s_nop 0
	v_addc_co_u32_e32 v13, vcc, 0, v1, vcc
	s_nop 0
	s_nop 0
	v_lshl_add_u64 v[2:3], v[0:1], 0, s[8:9]
	s_mov_b32 s8, 0x80000
	v_add_co_u32_e32 v20, vcc, s8, v0
	s_mov_b64 s[8:9], 0xc0000
	s_nop 0
	v_addc_co_u32_e32 v21, vcc, 0, v1, vcc
	s_nop 0
	v_lshl_add_u64 v[2:3], v[0:1], 0, s[8:9]
	s_mov_b32 s8, 0xc0000
	v_add_co_u32_e32 v28, vcc, s8, v0
	s_mov_b64 s[8:9], 0x100000
	s_nop 0
	v_addc_co_u32_e32 v29, vcc, 0, v1, vcc
	v_add_co_u32_e32 v38, vcc, s79, v0
	s_nop 0
	v_lshl_add_u64 v[2:3], v[0:1], 0, s[8:9]
	v_addc_co_u32_e32 v39, vcc, 0, v1, vcc
	s_mov_b64 s[8:9], 0x140000
	s_nop 0
	v_lshl_add_u64 v[2:3], v[0:1], 0, s[8:9]
	s_mov_b32 s8, 0x140000
	v_add_co_u32_e32 v46, vcc, s8, v0
	s_mov_b64 s[8:9], 0x180000
	s_nop 0
	v_addc_co_u32_e32 v47, vcc, 0, v1, vcc
	s_nop 0
	v_lshl_add_u64 v[2:3], v[0:1], 0, s[8:9]
	s_mov_b32 s8, 0x180000
	v_add_co_u32_e32 v54, vcc, s8, v0
	s_mov_b64 s[8:9], 0x1c0000
	s_nop 0
	v_addc_co_u32_e32 v55, vcc, 0, v1, vcc
	s_nop 0
	v_lshl_add_u64 v[2:3], v[0:1], 0, s[8:9]
	s_mov_b32 s8, 0x1c0000
	v_add_co_u32_e32 v0, vcc, s8, v0
	s_and_b32 s10, s10, 0x3f80
	s_nop 0
	v_addc_co_u32_e32 v1, vcc, 0, v1, vcc
	v_readlane_b32 s8, v252, 31
	s_add_u32 s8, s8, s28
	v_readlane_b32 s9, v252, 32
	s_addc_u32 s9, s9, 0
	s_lshl_b32 s11, s73, 4
	v_and_b32_e32 v108, 15, v99
	s_add_i32 s11, s11, s10
	v_or_b32_e32 v82, s11, v108
	v_mov_b64_e32 v[0:1], s[8:9]
	v_mad_i64_i32 v[0:1], s[8:9], v82, s70, v[0:1]
	v_and_b32_e32 v106, 48, v99
	v_mov_b32_e32 v107, v33
	v_lshl_add_u64 v[70:71], v[0:1], 0, v[106:107]
	v_add3_u32 v83, 0, v32, v102
	s_nop 0
	v_lshrrev_b32_e32 v105, 2, v98
	v_add3_u32 v4, s27, v32, v103
	v_lshrrev_b32_e32 v6, 1, v98
	v_and_b32_e32 v32, 24, v6
	v_mov_b64_e32 v[4:5], s[24:25]
	v_mad_i64_i32 v[4:5], s[8:9], v82, s70, v[4:5]
	v_lshl_add_u64 v[4:5], v[4:5], 0, s[28:29]
	v_lshl_add_u64 v[4:5], v[4:5], 0, v[32:33]
	s_mov_b64 s[8:9], 0x11103000
	v_lshl_add_u64 v[78:79], v[4:5], 0, s[8:9]
	s_mov_b32 s8, 0x11103000
	v_add_co_u32_e32 v94, vcc, s8, v4
	s_waitcnt lgkmcnt(0)
	s_nop 0
	v_addc_co_u32_e32 v95, vcc, 0, v5, vcc
	v_mov_b64_e32 v[0:1], v[228:229]
	v_mov_b64_e32 v[2:3], v[230:231]
	v_mov_b64_e32 v[62:63], v[232:233]
	v_mov_b64_e32 v[64:65], v[234:235]
	v_mov_b64_e32 v[66:67], v[236:237]
	v_mov_b64_e32 v[68:69], v[238:239]
	v_mov_b64_e32 v[70:71], v[240:241]
	v_mov_b64_e32 v[72:73], v[242:243]
	s_add_u32 s48, s72, 3
	s_and_b32 s48, s48, 7
	s_cmp_lt_u32 s72, 7
	s_cbranch_scc1 .Lpf_issue

.LBB0_1276:
	s_andn2_b64 vcc, exec, s[10:11]
	s_cbranch_vccnz .LBB0_1313
	s_lshl_b32 s13, s74, 12
	v_readlane_b32 s8, v252, 59
	s_or_b32 s83, s8, s13
	s_lshl_b32 s28, s12, 1
	v_readlane_b32 s8, v252, 15
	s_add_u32 s8, s8, s28
	v_readlane_b32 s9, v252, 16
	v_lshlrev_b32_e32 v0, 4, v99
	s_addc_u32 s9, s9, 0
	v_readlane_b32 s10, v252, 17
	v_and_b32_e32 v32, 0xf0, v0
	s_add_u32 s10, s10, s28
	v_readlane_b32 s11, v252, 18
	v_lshl_add_u64 v[16:17], s[8:9], 0, v[32:33]
	v_readlane_b32 s8, v252, 60
	s_addc_u32 s11, s11, 0
	v_and_b32_e32 v0, -16, v99
	s_add_i32 s8, s8, s13
	v_lshl_add_u64 v[18:19], s[10:11], 0, v[32:33]
	v_add_u32_e32 v24, s8, v0
	s_movk_i32 s8, 0x80
	v_readlane_b32 s10, v252, 57
	v_cmp_gt_i32_e32 vcc, s8, v104
	v_readlane_b32 s11, v252, 58
	v_mov_b32_e32 v25, s83
	s_and_b64 vcc, s[10:11], vcc
	v_cndmask_b32_e32 v2, v24, v25, vcc
	v_mad_i64_i32 v[0:1], s[8:9], v2, s70, v[16:17]
	v_mad_i64_i32 v[4:5], s[8:9], v2, s70, v[18:19]
	s_movk_i32 s8, 0x60
	s_nop 0
	v_cmp_gt_i32_e32 vcc, s8, v104
	v_add_u32_e32 v8, 0x200, v24
	s_and_b64 vcc, s[10:11], vcc
	v_cndmask_b32_e32 v10, v8, v25, vcc
	v_cmp_gt_i32_e32 vcc, 64, v104
	v_add_u32_e32 v20, 0x400, v24
	s_and_b64 vcc, s[10:11], vcc
	v_cndmask_b32_e32 v22, v20, v25, vcc
	v_mad_i64_i32 v[8:9], s[8:9], v10, s70, v[16:17]
	v_mad_i64_i32 v[12:13], s[8:9], v10, s70, v[18:19]
	v_mad_i64_i32 v[20:21], s[8:9], v22, s70, v[16:17]
	v_cmp_gt_i32_e32 vcc, 32, v104
	s_nop 0
	s_nop 0
	s_nop 0
	v_mad_i64_i32 v[22:23], s[8:9], v22, s70, v[18:19]
	v_add_u32_e32 v20, 0x600, v24
	s_and_b64 vcc, s[10:11], vcc
	v_cndmask_b32_e32 v22, v20, v25, vcc
	v_mad_i64_i32 v[20:21], s[8:9], v22, s70, v[16:17]
	v_cmp_gt_i32_e32 vcc, 0, v104
	v_mad_i64_i32 v[22:23], s[8:9], v22, s70, v[18:19]
	v_add_u32_e32 v20, 0x800, v24
	s_and_b64 vcc, s[10:11], vcc
	v_cndmask_b32_e32 v22, v20, v25, vcc
	v_mad_i64_i32 v[20:21], s[8:9], v22, s70, v[16:17]
	v_mad_i64_i32 v[22:23], s[8:9], v22, s70, v[18:19]
	s_movk_i32 s8, 0xffe0
	s_nop 0
	v_cmp_gt_i32_e32 vcc, s8, v104
	v_add_u32_e32 v20, 0xa00, v24
	s_and_b64 vcc, s[10:11], vcc
	v_cndmask_b32_e32 v22, v20, v25, vcc
	v_mad_i64_i32 v[20:21], s[8:9], v22, s70, v[16:17]
	v_mad_i64_i32 v[22:23], s[8:9], v22, s70, v[18:19]
	s_movk_i32 s8, 0xffc0
	s_nop 0
	v_cmp_gt_i32_e32 vcc, s8, v104
	v_add_u32_e32 v20, 0xc00, v24
	s_and_b64 vcc, s[10:11], vcc
	v_cndmask_b32_e32 v22, v20, v25, vcc
	v_mad_i64_i32 v[20:21], s[8:9], v22, s70, v[16:17]
	v_mad_i64_i32 v[22:23], s[8:9], v22, s70, v[18:19]
	s_movk_i32 s8, 0xffa0
	s_nop 0
	v_cmp_gt_i32_e32 vcc, s8, v104
	v_add_u32_e32 v20, 0xe00, v24
	s_and_b64 vcc, s[10:11], vcc
	v_cndmask_b32_e32 v20, v20, v25, vcc
	v_mad_i64_i32 v[16:17], s[8:9], v20, s70, v[16:17]
	v_mad_i64_i32 v[18:19], s[8:9], v20, s70, v[18:19]
	v_readlane_b32 s8, v252, 19
	s_add_u32 s8, s8, s28
	v_readlane_b32 s9, v252, 20
	s_addc_u32 s9, s9, 0
	s_lshl_b32 s10, s73, 8
	v_lshlrev_b32_e32 v16, 4, v98
	v_and_b32_e32 v16, 0xf0, v16
	s_add_i32 s10, s10, s83
	v_or_b32_e32 v18, s10, v16
	v_mov_b64_e32 v[16:17], s[8:9]
	v_mad_i64_i32 v[16:17], s[8:9], v18, s70, v[16:17]
	v_and_b32_e32 v82, 48, v99
	v_mov_b32_e32 v83, v33
	v_lshl_add_u64 v[28:29], v[16:17], 0, v[82:83]
	s_nop 0
	v_add3_u32 v83, 0, v32, v102
	s_add_i32 s8, s73, -2
	v_add_u32_e32 v82, 0, v82
	s_cmp_gt_u32 s8, -11
	s_cselect_b64 s[44:45], -1, 0
	s_cmp_lt_u32 s8, -10
	v_add3_u32 v0, s27, v32, v103
	v_and_b32_e32 v32, 15, v99
	v_mov_b32_e32 v0, 0
	v_mad_u32_u24 v83, v32, s33, v82
	v_mov_b32_e32 v8, 0
	v_mov_b32_e32 v9, 0
	v_mov_b32_e32 v10, 0
	v_mov_b32_e32 v11, 0
	v_mov_b32_e32 v12, 0
	v_mov_b32_e32 v13, 0
	v_mov_b32_e32 v14, 0
	v_mov_b32_e32 v15, 0
	s_waitcnt lgkmcnt(0)
	s_cselect_b32 s49, 1, 0
	v_mov_b64_e32 v[16:17], v[228:229]
	v_mov_b64_e32 v[18:19], v[230:231]
	v_mov_b64_e32 v[20:21], v[232:233]
	v_mov_b64_e32 v[22:23], v[234:235]
	v_mov_b64_e32 v[24:25], v[236:237]
	v_mov_b64_e32 v[26:27], v[238:239]
	v_mov_b64_e32 v[28:29], v[240:241]
	v_mov_b64_e32 v[30:31], v[242:243]
	s_add_u32 s48, s72, 3
	s_and_b32 s48, s48, 7
	s_cmp_lt_u32 s72, 7
	s_cbranch_scc1 .Lpf_issue

.LBB0_1314:
	s_andn2_b64 vcc, exec, s[10:11]
	s_cbranch_vccnz .LBB0_1351
	s_lshl_b32 s12, s74, 12
	v_readlane_b32 s8, v252, 63
	s_lshl_b32 s77, s75, 7
	s_or_b32 s83, s8, s12
	s_and_b32 s8, s77, 0x180
	s_lshl_b32 s28, s8, 1
	v_readlane_b32 s8, v252, 15
	s_add_u32 s8, s8, s28
	v_readlane_b32 s9, v252, 16
	v_lshlrev_b32_e32 v0, 4, v99
	s_addc_u32 s9, s9, 0
	v_readlane_b32 s10, v252, 17
	v_and_b32_e32 v32, 0xf0, v0
	s_add_u32 s10, s10, s28
	v_readlane_b32 s11, v252, 18
	v_lshl_add_u64 v[16:17], s[8:9], 0, v[32:33]
	v_readlane_b32 s8, v253, 0
	s_addc_u32 s11, s11, 0
	v_ashrrev_i32_e32 v84, 4, v99
	s_add_i32 s8, s8, s12
	v_lshl_add_u64 v[18:19], s[10:11], 0, v[32:33]
	v_lshl_add_u32 v24, v84, 2, s8
	s_movk_i32 s8, 0x80
	v_readlane_b32 s10, v252, 61
	v_cmp_gt_i32_e32 vcc, s8, v84
	v_readlane_b32 s11, v252, 62
	v_mov_b32_e32 v25, s83
	s_and_b64 vcc, s[10:11], vcc
	v_cndmask_b32_e32 v2, v24, v25, vcc
	v_mad_i64_i32 v[0:1], s[8:9], v2, s70, v[16:17]
	v_mad_i64_i32 v[4:5], s[8:9], v2, s70, v[18:19]
	s_movk_i32 s8, 0x60
	s_nop 0
	v_cmp_gt_i32_e32 vcc, s8, v84
	v_add_u32_e32 v8, 0x80, v24
	s_and_b64 vcc, s[10:11], vcc
	v_cndmask_b32_e32 v10, v8, v25, vcc
	v_cmp_gt_i32_e32 vcc, 64, v84
	v_add_u32_e32 v20, 0x100, v24
	s_and_b64 vcc, s[10:11], vcc
	v_cndmask_b32_e32 v22, v20, v25, vcc
	v_mad_i64_i32 v[8:9], s[8:9], v10, s70, v[16:17]
	v_mad_i64_i32 v[12:13], s[8:9], v10, s70, v[18:19]
	v_mad_i64_i32 v[20:21], s[8:9], v22, s70, v[16:17]
	v_cmp_gt_i32_e32 vcc, 32, v84
	s_nop 0
	s_nop 0
	s_nop 0
	v_mad_i64_i32 v[22:23], s[8:9], v22, s70, v[18:19]
	v_add_u32_e32 v20, 0x180, v24
	s_and_b64 vcc, s[10:11], vcc
	v_cndmask_b32_e32 v22, v20, v25, vcc
	v_mad_i64_i32 v[20:21], s[8:9], v22, s70, v[16:17]
	v_cmp_gt_i32_e32 vcc, 0, v84
	v_mad_i64_i32 v[22:23], s[8:9], v22, s70, v[18:19]
	v_add_u32_e32 v20, 0x200, v24
	s_and_b64 vcc, s[10:11], vcc
	v_cndmask_b32_e32 v22, v20, v25, vcc
	v_mad_i64_i32 v[20:21], s[8:9], v22, s70, v[16:17]
	v_mad_i64_i32 v[22:23], s[8:9], v22, s70, v[18:19]
	s_movk_i32 s8, 0xffe0
	s_nop 0
	v_cmp_gt_i32_e32 vcc, s8, v84
	v_add_u32_e32 v20, 0x280, v24
	s_and_b64 vcc, s[10:11], vcc
	v_cndmask_b32_e32 v22, v20, v25, vcc
	v_mad_i64_i32 v[20:21], s[8:9], v22, s70, v[16:17]
	v_mad_i64_i32 v[22:23], s[8:9], v22, s70, v[18:19]
	s_movk_i32 s8, 0xffc0
	s_nop 0
	v_cmp_gt_i32_e32 vcc, s8, v84
	v_add_u32_e32 v20, 0x300, v24
	s_and_b64 vcc, s[10:11], vcc
	v_cndmask_b32_e32 v22, v20, v25, vcc
	v_mad_i64_i32 v[20:21], s[8:9], v22, s70, v[16:17]
	v_mad_i64_i32 v[22:23], s[8:9], v22, s70, v[18:19]
	s_movk_i32 s8, 0xffa0
	s_nop 0
	v_cmp_gt_i32_e32 vcc, s8, v84
	v_add_u32_e32 v20, 0x380, v24
	s_and_b64 vcc, s[10:11], vcc
	v_cndmask_b32_e32 v20, v20, v25, vcc
	v_mad_i64_i32 v[16:17], s[8:9], v20, s70, v[16:17]
	v_mad_i64_i32 v[18:19], s[8:9], v20, s70, v[18:19]
	v_readlane_b32 s8, v252, 23
	s_add_u32 s8, s8, s28
	v_readlane_b32 s9, v252, 24
	s_addc_u32 s9, s9, 0
	s_and_b32 s10, s76, 0xffffffc0
	v_lshlrev_b32_e32 v16, 2, v98
	s_add_i32 s10, s10, s83
	v_and_or_b32 v18, v16, 60, s10
	v_mov_b64_e32 v[16:17], s[8:9]
	v_mad_i64_i32 v[16:17], s[8:9], v18, s70, v[16:17]
	v_and_b32_e32 v82, 48, v99
	v_mov_b32_e32 v83, v33
	v_lshl_add_u64 v[28:29], v[16:17], 0, v[82:83]
	s_nop 0
	v_mul_lo_u32 v83, v84, s33
	v_add3_u32 v83, 0, v32, v83
	s_movk_i32 s8, 0x120
	v_add_u32_e32 v82, 0, v82
	v_mul_lo_u32 v0, v84, s8
	s_add_i32 s8, s73, -2
	v_add3_u32 v0, s27, v32, v0
	v_and_b32_e32 v32, 15, v99
	s_cmp_gt_u32 s8, -11
	v_mov_b32_e32 v0, 0
	s_cselect_b64 s[44:45], -1, 0
	s_cmp_lt_u32 s8, -10
	v_mad_u32_u24 v83, v32, s33, v82
	v_mov_b32_e32 v8, 0
	v_mov_b32_e32 v9, 0
	v_mov_b32_e32 v10, 0
	v_mov_b32_e32 v11, 0
	v_mov_b32_e32 v12, 0
	v_mov_b32_e32 v13, 0
	v_mov_b32_e32 v14, 0
	v_mov_b32_e32 v15, 0
	s_waitcnt lgkmcnt(0)
	s_cselect_b32 s49, 1, 0
	v_mov_b64_e32 v[16:17], v[228:229]
	v_mov_b64_e32 v[18:19], v[230:231]
	v_mov_b64_e32 v[20:21], v[232:233]
	v_mov_b64_e32 v[22:23], v[234:235]
	v_mov_b64_e32 v[24:25], v[236:237]
	v_mov_b64_e32 v[26:27], v[238:239]
	v_mov_b64_e32 v[28:29], v[240:241]
	v_mov_b64_e32 v[30:31], v[242:243]
	s_add_u32 s48, s72, 3
	s_and_b32 s48, s48, 7
	s_cmp_lt_u32 s72, 7
	s_cbranch_scc1 .Lpf_issue

.LBB0_1352:
	s_andn2_b64 vcc, exec, s[10:11]
	s_cbranch_vccnz .LBB0_1271
	s_lshl_b32 s8, s74, 12
	v_readlane_b32 s9, v253, 1
	s_or_b32 s12, s8, s9
	v_readlane_b32 s9, v253, 2
	s_lshl_b32 s74, s75, 7
	s_add_i32 s13, s9, s8
	s_and_b32 s8, s74, 0x180
	s_lshl_b32 s28, s8, 1
	v_readlane_b32 s8, v252, 15
	s_add_u32 s8, s8, s28
	v_readlane_b32 s9, v252, 16
	s_addc_u32 s9, s9, 0
	v_readlane_b32 s10, v252, 17
	s_add_u32 s10, s10, s28
	v_readlane_b32 s11, v252, 18
	v_lshlrev_b32_e32 v0, 4, v99
	s_addc_u32 s11, s11, 0
	v_and_b32_e32 v32, 0xf0, v0
	v_ashrrev_i32_e32 v83, 4, v99
	v_lshl_add_u64 v[16:17], s[8:9], 0, v[32:33]
	v_lshl_add_u64 v[18:19], s[10:11], 0, v[32:33]
	s_movk_i32 s8, 0x80
	v_readlane_b32 s10, v253, 3
	v_cmp_gt_i32_e32 vcc, s8, v83
	v_readlane_b32 s11, v253, 4
	v_add_u32_e32 v24, s13, v83
	v_mov_b32_e32 v25, s12
	s_and_b64 vcc, s[10:11], vcc
	v_cndmask_b32_e32 v2, v24, v25, vcc
	v_mad_i64_i32 v[0:1], s[8:9], v2, s70, v[16:17]
	v_mad_i64_i32 v[4:5], s[8:9], v2, s70, v[18:19]
	s_movk_i32 s8, 0x60
	s_nop 0
	v_cmp_gt_i32_e32 vcc, s8, v83
	v_add_u32_e32 v8, 32, v24
	s_and_b64 vcc, s[10:11], vcc
	v_cndmask_b32_e32 v10, v8, v25, vcc
	v_cmp_gt_i32_e32 vcc, 64, v83
	v_add_u32_e32 v20, 64, v24
	s_and_b64 vcc, s[10:11], vcc
	v_cndmask_b32_e32 v22, v20, v25, vcc
	v_mad_i64_i32 v[8:9], s[8:9], v10, s70, v[16:17]
	v_mad_i64_i32 v[12:13], s[8:9], v10, s70, v[18:19]
	v_mad_i64_i32 v[20:21], s[8:9], v22, s70, v[16:17]
	v_cmp_gt_i32_e32 vcc, 32, v83
	s_nop 0
	s_nop 0
	s_nop 0
	v_mad_i64_i32 v[22:23], s[8:9], v22, s70, v[18:19]
	v_add_u32_e32 v20, 0x60, v24
	s_and_b64 vcc, s[10:11], vcc
	v_cndmask_b32_e32 v22, v20, v25, vcc
	v_mad_i64_i32 v[20:21], s[8:9], v22, s70, v[16:17]
	v_cmp_gt_i32_e32 vcc, 0, v83
	v_mad_i64_i32 v[22:23], s[8:9], v22, s70, v[18:19]
	v_add_u32_e32 v20, 0x80, v24
	s_and_b64 vcc, s[10:11], vcc
	v_cndmask_b32_e32 v22, v20, v25, vcc
	v_mad_i64_i32 v[20:21], s[8:9], v22, s70, v[16:17]
	v_mad_i64_i32 v[22:23], s[8:9], v22, s70, v[18:19]
	s_movk_i32 s8, 0xffe0
	s_nop 0
	v_cmp_gt_i32_e32 vcc, s8, v83
	v_add_u32_e32 v20, 0xa0, v24
	s_and_b64 vcc, s[10:11], vcc
	v_cndmask_b32_e32 v22, v20, v25, vcc
	v_mad_i64_i32 v[20:21], s[8:9], v22, s70, v[16:17]
	v_mad_i64_i32 v[22:23], s[8:9], v22, s70, v[18:19]
	s_movk_i32 s8, 0xffc0
	s_nop 0
	v_cmp_gt_i32_e32 vcc, s8, v83
	v_add_u32_e32 v20, 0xc0, v24
	s_and_b64 vcc, s[10:11], vcc
	v_cndmask_b32_e32 v22, v20, v25, vcc
	v_mad_i64_i32 v[20:21], s[8:9], v22, s70, v[16:17]
	v_mad_i64_i32 v[22:23], s[8:9], v22, s70, v[18:19]
	s_movk_i32 s8, 0xffa0
	s_nop 0
	v_cmp_gt_i32_e32 vcc, s8, v83
	v_add_u32_e32 v20, 0xe0, v24
	s_and_b64 vcc, s[10:11], vcc
	v_cndmask_b32_e32 v20, v20, v25, vcc
	v_mad_i64_i32 v[16:17], s[8:9], v20, s70, v[16:17]
	v_mad_i64_i32 v[18:19], s[8:9], v20, s70, v[18:19]
	v_readlane_b32 s8, v252, 27
	s_add_u32 s8, s8, s28
	v_readlane_b32 s9, v252, 28
	v_and_b32_e32 v85, 15, v99
	s_addc_u32 s9, s9, 0
	v_lshl_or_b32 v82, s73, 4, v85
	v_add_u32_e32 v84, s12, v82
	v_mov_b64_e32 v[16:17], s[8:9]
	v_mad_i64_i32 v[16:17], s[8:9], v84, s70, v[16:17]
	v_and_b32_e32 v86, 48, v99
	v_mov_b32_e32 v87, v33
	v_lshl_add_u64 v[28:29], v[16:17], 0, v[86:87]
	s_nop 0
	v_mul_lo_u32 v87, v83, s33
	v_add3_u32 v87, 0, v32, v87
	s_movk_i32 s8, 0x120
	v_mul_lo_u32 v0, v83, s8
	s_add_i32 s8, s73, -2
	v_add3_u32 v0, s27, v32, v0
	v_add_u32_e32 v32, 0, v86
	s_cmp_gt_u32 s8, -11
	v_mov_b32_e32 v0, 0
	s_cselect_b64 s[44:45], -1, 0
	s_cmp_lt_u32 s8, -10
	v_mad_u32_u24 v83, v85, s33, v32
	v_mov_b32_e32 v8, 0
	v_mov_b32_e32 v9, 0
	v_mov_b32_e32 v10, 0
	v_mov_b32_e32 v11, 0
	v_mov_b32_e32 v12, 0
	v_mov_b32_e32 v13, 0
	v_mov_b32_e32 v14, 0
	v_mov_b32_e32 v15, 0
	s_waitcnt lgkmcnt(0)
	s_cselect_b32 s49, 1, 0
	v_mov_b64_e32 v[16:17], v[228:229]
	v_mov_b64_e32 v[18:19], v[230:231]
	v_mov_b64_e32 v[20:21], v[232:233]
	v_mov_b64_e32 v[22:23], v[234:235]
	v_mov_b64_e32 v[24:25], v[236:237]
	v_mov_b64_e32 v[26:27], v[238:239]
	v_mov_b64_e32 v[28:29], v[240:241]
	v_mov_b64_e32 v[30:31], v[242:243]
	s_add_u32 s48, s72, 3
	s_and_b32 s48, s48, 7
	s_cmp_lt_u32 s72, 7
	s_cbranch_scc1 .Lpf_issue

.Lpf_loads:
	v_add_u32_e32 v244, v244, v227
	v_bfe_u32 v227, v218, 4, 2
	v_lshl_add_u32 v245, v227, 4, v245
	global_load_dwordx4 v[154:157], v244, s[56:57]
	global_load_dwordx4 v[158:161], v244, s[56:57] offset:1024
	s_add_u32 s56, s56, s62
	s_addc_u32 s57, s57, 0
	global_load_dwordx4 v[162:165], v244, s[56:57]
	global_load_dwordx4 v[166:169], v244, s[56:57] offset:1024
	s_add_u32 s56, s56, s62
	s_addc_u32 s57, s57, 0
	global_load_dwordx4 v[170:173], v244, s[56:57]
	global_load_dwordx4 v[174:177], v244, s[56:57] offset:1024
	s_add_u32 s56, s56, s62
	s_addc_u32 s57, s57, 0
	global_load_dwordx4 v[178:181], v244, s[56:57]
	global_load_dwordx4 v[182:185], v244, s[56:57] offset:1024
	global_load_dwordx4 v[186:189], v244, s[58:59]
	global_load_dwordx4 v[190:193], v244, s[58:59] offset:1024
	s_add_u32 s58, s58, s62
	s_addc_u32 s59, s59, 0
	global_load_dwordx4 v[194:197], v244, s[58:59]
	global_load_dwordx4 v[198:201], v244, s[58:59] offset:1024
	s_add_u32 s58, s58, s62
	s_addc_u32 s59, s59, 0
	global_load_dwordx4 v[202:205], v244, s[58:59]
	global_load_dwordx4 v[206:209], v244, s[58:59] offset:1024
	s_add_u32 s58, s58, s62
	s_addc_u32 s59, s59, 0
	global_load_dwordx4 v[210:213], v244, s[58:59]
	global_load_dwordx4 v[214:217], v244, s[58:59] offset:1024
	global_load_dwordx4 v[228:231], v245, s[60:61]
	global_load_dwordx4 v[232:235], v245, s[60:61] offset:64
	global_load_dwordx4 v[236:239], v245, s[60:61] offset:128
	global_load_dwordx4 v[240:243], v245, s[60:61] offset:192
	s_cmp_eq_u32 s48, 2
	s_cbranch_scc1 .Lpf_ret_pre
	s_cmp_eq_u32 s48, 1
	s_cbranch_scc1 .Lpf_ret_k0
	s_cmp_eq_u32 s48, 0
	s_cbranch_scc1 .Lpf_ret_k3
	s_cmp_lt_u32 s48, 5
	s_cbranch_scc1 .Lpf_ret_k1
	s_cmp_lt_u32 s48, 7
	s_cbranch_scc1 .Lpf_ret_k2
	s_branch .Lpf_ret_k3

.LBB0_1441:
	s_or_b64 exec, exec, s[10:11]
	v_mov_b32_e32 v1, v218
	v_readlane_b32 s2, v253, 5
	s_waitcnt lgkmcnt(0)
	s_barrier
	v_readlane_b32 s8, v252, 11
	s_nop 0
	s_cmp_eq_u32 s8, 0
	s_cbranch_scc1 .Lp3_entry
	s_nop 0
	v_add_u32_e32 v0, s2, v1
	v_cmp_gt_i32_e32 vcc, s79, v0
	s_and_saveexec_b64 s[30:31], vcc
	s_cbranch_execz .LBB0_1458
	v_readlane_b32 s2, v254, 52
	s_mov_b64 s[34:35], 0
	s_nop 0
	v_lshl_add_u32 v132, v1, 3, s2
	s_branch .LBB0_1444

.Lp3_entry:
	v_readlane_b32 s8, v253, 10
	v_readlane_b32 s9, v253, 11
	s_waitcnt vmcnt(2)
	v_mov_b32_e32 v12, v218
	s_waitcnt lgkmcnt(0)
	v_cndmask_b32_e64 v0, 0, 1, s[8:9]
	s_barrier
	v_cmp_ne_u32_e64 s[10:11], 1, v0
	s_andn2_b64 vcc, exec, s[8:9]
	v_readfirstlane_b32 s8, v12
	s_cbranch_vccnz .LBB0_1575
	v_lshlrev_b32_e32 v0, 4, v12
	v_add_u32_e32 v1, 0x2000, v0
	v_ashrrev_i32_e32 v2, 31, v1
	v_lshrrev_b32_e32 v2, 22, v2
	v_add_u32_e32 v2, v1, v2
	v_ashrrev_i32_e32 v4, 10, v2
	v_mul_i32_i24_e32 v2, 0x400, v4
	v_sub_u32_e32 v1, v1, v2
	v_lshrrev_b32_e32 v2, 4, v1
	v_bitop3_b32 v1, v2, v1, 32 bitop3:0x6c
	v_ashrrev_i32_e32 v2, 31, v1
	v_readlane_b32 s12, v255, 4
	v_lshrrev_b32_e32 v2, 26, v2
	v_readlane_b32 s13, v255, 5
	v_add_u32_e32 v2, v1, v2
	v_lshlrev_b32_e32 v3, 3, v4
	s_lshl_b64 s[12:13], s[12:13], 22
	v_readlane_b32 s2, v253, 6
	v_ashrrev_i32_e32 v5, 6, v2
	v_and_b32_e32 v3, -16, v3
	s_add_u32 s2, s2, s12
	v_readlane_b32 s9, v253, 7
	v_add_u32_e32 v3, v5, v3
	s_addc_u32 s83, s9, s13
	v_and_b32_e32 v6, 3, v5
	s_mov_b32 s13, 0x3fffe0
	v_lshrrev_b32_e32 v7, 2, v3
	s_waitcnt vmcnt(1)
	v_lshlrev_b32_e32 v8, 1, v3
	v_and_b32_e32 v2, 0xc0, v2
	v_and_or_b32 v6, v3, s13, v6
	v_and_b32_e32 v7, 4, v7
	v_and_b32_e32 v8, 24, v8
	v_sub_u32_e32 v1, v1, v2
	v_or3_b32 v8, v6, v7, v8
	v_lshlrev_b32_e32 v6, 5, v4
	v_ashrrev_i16_sdwa v1, v224, sext(v1) dst_sel:DWORD dst_unused:UNUSED_PAD src0_sel:DWORD src1_sel:BYTE_0
	v_and_b32_e32 v6, 32, v6
	v_bfe_i32 v7, v1, 0, 16
	v_add_u32_e32 v1, v6, v7
	v_lshlrev_b32_e32 v2, 1, v1
	s_movk_i32 s14, 0x2a00
	v_lshl_add_u32 v166, v8, 10, v2
	v_mul_lo_u32 v2, v3, s14
	v_add_lshl_u32 v168, v1, v2, 1
	v_bfe_i32 v1, v12, 27, 1
	v_lshrrev_b32_e32 v1, 22, v1
	v_add_u32_e32 v1, v0, v1
	v_and_b32_e32 v1, 0xfffffc00, v1
	v_sub_u32_e32 v0, v0, v1
	v_lshrrev_b32_e32 v1, 4, v0
	v_ashrrev_i32_e32 v2, 31, v12
	v_bitop3_b32 v0, v1, v0, 32 bitop3:0x6c
	v_lshrrev_b32_e32 v2, 26, v2
	v_ashrrev_i32_e32 v1, 31, v0
	v_add_u32_e32 v2, v12, v2
	v_lshrrev_b32_e32 v1, 26, v1
	v_ashrrev_i32_e32 v9, 6, v2
	v_add_u32_e32 v1, v0, v1
	v_lshlrev_b32_e32 v2, 3, v9
	v_ashrrev_i32_e32 v8, 6, v1
	v_and_b32_e32 v2, -16, v2
	v_add_u32_e32 v2, v8, v2
	v_and_b32_e32 v3, 3, v8
	v_lshrrev_b32_e32 v10, 2, v2
	v_lshlrev_b32_e32 v11, 1, v2
	v_and_b32_e32 v1, 0xc0, v1
	v_and_or_b32 v3, v2, s13, v3
	v_and_b32_e32 v10, 4, v10
	v_and_b32_e32 v11, 24, v11
	v_sub_u32_e32 v0, v0, v1
	v_or3_b32 v3, v3, v10, v11
	v_lshlrev_b32_e32 v10, 5, v9
	v_ashrrev_i16_sdwa v0, v224, sext(v0) dst_sel:DWORD dst_unused:UNUSED_PAD src0_sel:DWORD src1_sel:BYTE_0
	v_and_b32_e32 v10, 32, v10
	v_bfe_i32 v11, v0, 0, 16
	v_add_u32_e32 v0, v10, v11
	s_ashr_i32 s9, s8, 6
	v_lshlrev_b32_e32 v1, 1, v0
	s_ashr_i32 s12, s8, 8
	s_lshl_b32 s84, s9, 10
	v_lshl_add_u32 v32, v3, 10, v1
	v_mul_lo_u32 v1, v2, s14
	v_readlane_b32 s14, v253, 51
	v_readlane_b32 s15, v253, 52
	s_add_u32 s74, s2, s14
	s_addc_u32 s75, s83, s15
	s_add_i32 s85, s84, 0
	s_add_i32 m0, s85, 0x10000
	v_add_lshl_u32 v170, v0, v1, 1
	global_load_lds_dwordx4 v32, s[74:75]
	s_add_i32 m0, s85, 0x12000
	s_add_u32 s14, s74, 0x20000
	global_load_lds_dwordx4 v166, s[74:75]
	s_addc_u32 s15, s75, 0
	s_add_i32 m0, s85, 0x14000
	s_add_i32 s86, s85, 0x2000
	global_load_lds_dwordx4 v32, s[14:15]
	s_add_i32 m0, s85, 0x16000
	s_add_i32 s87, s85, 0x4000
	global_load_lds_dwordx4 v166, s[14:15]
	v_readlane_b32 s14, v253, 53
	s_mov_b32 m0, s85
	v_readlane_b32 s15, v253, 54
	s_add_i32 s88, s85, 0x6000
	v_mov_b32_e32 v167, v33
	s_cmp_eq_u32 s12, 1
	v_lshl_add_u64 v[0:1], s[74:75], 0, v[32:33]
	s_cselect_b64 s[16:17], -1, 0
	global_load_lds_dwordx4 v170, s[14:15]
	s_mov_b32 m0, s86
	s_cmp_lg_u32 s12, 1
	global_load_lds_dwordx4 v168, s[14:15]
	v_readlane_b32 s14, v253, 55
	s_mov_b32 m0, s87
	v_readlane_b32 s15, v253, 56
	v_lshl_add_u64 v[2:3], s[74:75], 0, v[166:167]
	s_nop 3
	global_load_lds_dwordx4 v170, s[14:15]
	s_mov_b32 m0, s88
	s_nop 0
	global_load_lds_dwordx4 v168, s[14:15]
	s_cbranch_scc1 .LBB0_1513
	s_barrier
